# GEMM K-loops: back edge rotated in front of the last barrier; loop-invariant LDS read bases kept in v[242:245] (4 VALU per iteration removed from load-segment heads)
# speedup vs baseline: 1.0068x; 1.0068x over previous
; #define PG8_STAGE(bufoff, gbase, voff) do { _Pragma("unroll") for (int _i = 0; _i < 2; ++_i) \
;         __builtin_amdgcn_global_load_lds((const unsigned*)((const char*)(gbase) + (voff)[_i]), (PG8_LAS unsigned*)(lds + (bufoff) + ldsw + _i * 8192), 16, 0, 0); } while (0)
; #define PG8_LDA(dst, b, h) do { _Pragma("unroll") for (int m = 0; m < 4; ++m) _Pragma("unroll") for (int k = 0; k < 2; ++k) dst[m][k] = *(const PG8_LAS bf16x8*)(lds + PG8_SA(b, h) + aoff + m * 2048 + k * 1024); } while (0)
; #define PG8_LDB(dst, b, h) do { _Pragma("unroll") for (int n = 0; n < 2; ++n) _Pragma("unroll") for (int k = 0; k < 2; ++k) dst[n][k] = *(const PG8_LAS bf16x8*)(lds + PG8_SB(b, h) + boff + n * 2048 + k * 1024); } while (0)
; #define PG8_SCHED __builtin_amdgcn_sched_barrier(0)
; template <class Epi, class Sched, bool ALIGN_EPI = false, bool SP2 = false>
; __device__ __forceinline__ void gemm_phase(PG8_LAS unsigned char* lds, const Gemm g, const Sched& S, const Epi& E) {
;     ...
;         const bool has_next = S.next(ui + 1, nxt);
;         const char* nA = has_next ? (const char*)g.A + (size_t)nxt.pm * tstep : cA; const char* nB = has_next ? (const char*)g.Bt + (size_t)nxt.pn * tstep : cB;
;         for (int t = 0; t < nt; t += 2) {
;             const bool last = (t == nt - 2);
;             const char* a1 = cA + (size_t)(t + 1) * kstep;
;             const char* a2 = last ? nA : cA + (size_t)(t + 2) * kstep; const char* b2 = last ? nB : cB + (size_t)(t + 2) * kstep;
;             const char* a3 = a2 + kstep; const char* b3 = b2 + kstep;
;             if (last && has_next) S.a_ready(nxt);
;             if constexpr (SP2) {
;             PG8_LDB(B0, 0, 0); PG8_LDB(B1, 0, 1); PG8_SCHED; PG8_LDA(At, 0, 0); PG8_STAGE(PG8_SA(1, 1), a1 + hstep, voffA);
;     ...
; #pragma unroll
;         for (int a = 0; a < 2; ++a)
; #pragma unroll
;             for (int b = 0; b < 2; ++b)
; #pragma unroll
;                 for (int m = 0; m < 4; ++m)
; #pragma unroll
;                     for (int n = 0; n < 2; ++n) acc[a][b][m][n] = (f32x4){0.f, 0.f, 0.f, 0.f};
;         cur = nxt; cA = nA; cB = nB; ++ui;
.LBB0_179:
	s_ashr_i32 s37, s36, 31
	s_lshl_b64 s[42:43], s[36:37], 20
	s_add_u32 s42, s16, s42
	s_addc_u32 s43, s17, s43
	s_and_b64 s[44:45], s[40:41], exec
	s_cselect_b32 s25, s43, s79
	s_cselect_b32 s27, s42, s78
	s_ashr_i32 s23, s22, 31
	s_lshl_b64 s[44:45], s[22:23], 20
	s_add_u32 s44, s4, s44
	s_addc_u32 s45, s5, s45
	s_and_b64 s[82:83], s[40:41], exec
	s_cselect_b32 s23, s45, s81
	s_cselect_b32 s37, s44, s80
	s_add_u32 s78, s78, 0x80080
	s_addc_u32 s79, s79, 0
	s_add_u32 s47, s80, 0x100
	v_mov_b32_e32 v2, 0
	s_addc_u32 s51, s81, 0
	s_mov_b32 s52, -2
	v_mov_b32_e32 v3, v2
	v_mov_b32_e32 v4, v2
	v_mov_b32_e32 v5, v2
	v_mov_b32_e32 v6, v2
	v_mov_b32_e32 v7, v2
	v_mov_b32_e32 v8, v2
	v_mov_b32_e32 v9, v2
	v_mov_b32_e32 v18, v2
	v_mov_b32_e32 v19, v2
	v_mov_b32_e32 v20, v2
	v_mov_b32_e32 v21, v2
	v_mov_b32_e32 v22, v2
	v_mov_b32_e32 v23, v2
	v_mov_b32_e32 v24, v2
	v_mov_b32_e32 v25, v2
	v_mov_b32_e32 v34, v2
	v_mov_b32_e32 v35, v2
	v_mov_b32_e32 v36, v2
	v_mov_b32_e32 v37, v2
	v_mov_b32_e32 v38, v2
	v_mov_b32_e32 v39, v2
	v_mov_b32_e32 v40, v2
	v_mov_b32_e32 v41, v2
	v_mov_b32_e32 v50, v2
	v_mov_b32_e32 v51, v2
	v_mov_b32_e32 v52, v2
	v_mov_b32_e32 v53, v2
	v_mov_b32_e32 v54, v2
	v_mov_b32_e32 v55, v2
	v_mov_b32_e32 v56, v2
	v_mov_b32_e32 v57, v2
	v_mov_b32_e32 v10, v2
	v_mov_b32_e32 v11, v2
	v_mov_b32_e32 v12, v2
	v_mov_b32_e32 v13, v2
	v_mov_b32_e32 v14, v2
	v_mov_b32_e32 v15, v2
	v_mov_b32_e32 v16, v2
	v_mov_b32_e32 v17, v2
	v_mov_b32_e32 v26, v2
	v_mov_b32_e32 v27, v2
	v_mov_b32_e32 v28, v2
	v_mov_b32_e32 v29, v2
	v_mov_b32_e32 v30, v2
	v_mov_b32_e32 v31, v2
	v_mov_b32_e32 v32, v2
	v_mov_b32_e32 v33, v2
	v_mov_b32_e32 v42, v2
	v_mov_b32_e32 v43, v2
	v_mov_b32_e32 v44, v2
	v_mov_b32_e32 v45, v2
	v_mov_b32_e32 v46, v2
	v_mov_b32_e32 v47, v2
	v_mov_b32_e32 v48, v2
	v_mov_b32_e32 v49, v2
	v_mov_b32_e32 v58, v2
	v_mov_b32_e32 v59, v2
	v_mov_b32_e32 v60, v2
	v_mov_b32_e32 v61, v2
	v_mov_b32_e32 v62, v2
	v_mov_b32_e32 v63, v2
	v_mov_b32_e32 v64, v2
	v_mov_b32_e32 v65, v2
	v_mov_b32_e32 v66, v2
	v_mov_b32_e32 v67, v2
	v_mov_b32_e32 v68, v2
	v_mov_b32_e32 v69, v2
	v_mov_b32_e32 v70, v2
	v_mov_b32_e32 v71, v2
	v_mov_b32_e32 v72, v2
	v_mov_b32_e32 v73, v2
	v_mov_b32_e32 v82, v2
	v_mov_b32_e32 v83, v2
	v_mov_b32_e32 v84, v2
	v_mov_b32_e32 v85, v2
	v_mov_b32_e32 v86, v2
	v_mov_b32_e32 v87, v2
	v_mov_b32_e32 v88, v2
	v_mov_b32_e32 v89, v2
	v_mov_b32_e32 v98, v2
	v_mov_b32_e32 v99, v2
	v_mov_b32_e32 v100, v2
	v_mov_b32_e32 v101, v2
	v_mov_b32_e32 v102, v2
	v_mov_b32_e32 v103, v2
	v_mov_b32_e32 v104, v2
	v_mov_b32_e32 v105, v2
	v_mov_b32_e32 v114, v2
	v_mov_b32_e32 v115, v2
	v_mov_b32_e32 v116, v2
	v_mov_b32_e32 v117, v2
	v_mov_b32_e32 v118, v2
	v_mov_b32_e32 v119, v2
	v_mov_b32_e32 v120, v2
	v_mov_b32_e32 v121, v2
	v_mov_b32_e32 v74, v2
	v_mov_b32_e32 v75, v2
	v_mov_b32_e32 v76, v2
	v_mov_b32_e32 v77, v2
	v_mov_b32_e32 v78, v2
	v_mov_b32_e32 v79, v2
	v_mov_b32_e32 v80, v2
	v_mov_b32_e32 v81, v2
	v_mov_b32_e32 v90, v2
	v_mov_b32_e32 v91, v2
	v_mov_b32_e32 v92, v2
	v_mov_b32_e32 v93, v2
	v_mov_b32_e32 v94, v2
	v_mov_b32_e32 v95, v2
	v_mov_b32_e32 v96, v2
	v_mov_b32_e32 v97, v2
	v_mov_b32_e32 v106, v2
	v_mov_b32_e32 v107, v2
	v_mov_b32_e32 v108, v2
	v_mov_b32_e32 v109, v2
	v_mov_b32_e32 v110, v2
	v_mov_b32_e32 v111, v2
	v_mov_b32_e32 v112, v2
	v_mov_b32_e32 v113, v2
	v_mov_b32_e32 v122, v2
	v_mov_b32_e32 v123, v2
	v_mov_b32_e32 v124, v2
	v_mov_b32_e32 v125, v2
	v_mov_b32_e32 v126, v2
	v_mov_b32_e32 v127, v2
	v_mov_b32_e32 v128, v2
	v_mov_b32_e32 v129, v2
	v_add_u32_e32 v242, s88, v177
	v_add_u32_e32 v243, s89, v177
	v_add_u32_e32 v244, s90, v177
	v_add_u32_e32 v245, 0x1c000, v177
.LBB0_180:
	ds_read_b128 v[130:133], v242
	ds_read_b128 v[134:137], v242 offset:1024
	ds_read_b128 v[138:141], v242 offset:2048
	ds_read_b128 v[142:145], v242 offset:3072
	ds_read_b128 v[146:149], v243
	ds_read_b128 v[150:153], v243 offset:1024
	ds_read_b128 v[164:167], v243 offset:2048
	ds_read_b128 v[168:171], v243 offset:3072
	s_add_u32 s80, s78, 0xfff80080
	s_addc_u32 s81, s79, -1
	s_cmp_eq_u32 s52, 28
	s_cselect_b32 s83, s25, s81
	s_cselect_b32 s82, s27, s80
	s_cselect_b32 s81, s23, s51
	s_cselect_b32 s80, s37, s47
	v_lshl_add_u64 v[204:205], s[78:79], 0, v[160:161]
	s_add_i32 m0, s7, 0xc000
	ds_read_b128 v[172:175], v179
	ds_read_b128 v[180:183], v179 offset:1024
	ds_read_b128 v[184:187], v179 offset:2048
	ds_read_b128 v[188:191], v179 offset:3072
	ds_read_b128 v[192:195], v179 offset:4096
	ds_read_b128 v[196:199], v179 offset:5120
	ds_read_b128 v[200:203], v179 offset:6144
	ds_read_b128 v[208:211], v179 offset:7168
	global_load_lds_dwordx4 v[204:205], off
	s_add_i32 m0, s7, 0xe000
	v_lshl_add_u64 v[204:205], s[78:79], 0, v[162:163]
	global_load_lds_dwordx4 v[204:205], off
	s_waitcnt vmcnt(8)
	s_waitcnt lgkmcnt(0)
	s_barrier
; #define PG8_STAGE(bufoff, gbase, voff) do { _Pragma("unroll") for (int _i = 0; _i < 2; ++_i) \
;         __builtin_amdgcn_global_load_lds((const unsigned*)((const char*)(gbase) + (voff)[_i]), (PG8_LAS unsigned*)(lds + (bufoff) + ldsw + _i * 8192), 16, 0, 0); } while (0)
; #define PG8_LDA(dst, b, h) do { _Pragma("unroll") for (int m = 0; m < 4; ++m) _Pragma("unroll") for (int k = 0; k < 2; ++k) dst[m][k] = *(const PG8_LAS bf16x8*)(lds + PG8_SA(b, h) + aoff + m * 2048 + k * 1024); } while (0)
; #define PG8_LDB(dst, b, h) do { _Pragma("unroll") for (int n = 0; n < 2; ++n) _Pragma("unroll") for (int k = 0; k < 2; ++k) dst[n][k] = *(const PG8_LAS bf16x8*)(lds + PG8_SB(b, h) + boff + n * 2048 + k * 1024); } while (0)
; #define PG8_MMA(ai, bj, At, Bt) do { __builtin_amdgcn_s_setprio(1); _Pragma("unroll") for (int m = 0; m < 4; ++m) _Pragma("unroll") for (int n = 0; n < 2; ++n) _Pragma("unroll") for (int k = 0; k < 2; ++k) \
;         acc[ai][bj][m][n] = __builtin_amdgcn_mfma_f32_16x16x32_bf16(Bt[n][k], At[m][k], acc[ai][bj][m][n], 0, 0, 0); __builtin_amdgcn_s_setprio(0); } while (0)
; #define PG8_WAIT_V(n) asm volatile("s_waitcnt vmcnt(" #n ")" ::: "memory")
; #define PG8_WAIT_L(n) asm volatile("s_waitcnt lgkmcnt(" #n ")" ::: "memory")
; #define PG8_BAR __builtin_amdgcn_s_barrier()
; #define PG8_SCHED __builtin_amdgcn_sched_barrier(0)
; template <class Epi, class Sched, bool ALIGN_EPI = false, bool SP2 = false>
; __device__ __forceinline__ void gemm_phase(PG8_LAS unsigned char* lds, const Gemm g, const Sched& S, const Epi& E) {
;     ...
;             PG8_LDB(B0, 0, 0); PG8_LDB(B1, 0, 1); PG8_SCHED; PG8_LDA(At, 0, 0); PG8_STAGE(PG8_SA(1, 1), a1 + hstep, voffA);
;             PG8_WAIT_V(8); PG8_WAIT_L(0); PG8_BAR; PG8_MMA(0, 0, At, B0); PG8_MMA(0, 1, At, B1); PG8_BAR; PG8_SCHED;
;             PG8_LDA(At, 0, 1); PG8_STAGE(PG8_SB(0, 0), b2, voffB); PG8_STAGE(PG8_SB(0, 1), b2 + hstep, voffB); PG8_STAGE(PG8_SA(0, 0), a2, voffA);
;             PG8_WAIT_V(8); PG8_WAIT_L(0); PG8_BAR; PG8_MMA(1, 0, At, B0); PG8_MMA(1, 1, At, B1); PG8_BAR; PG8_SCHED;
	s_setprio 1
	v_mfma_f32_16x16x32_bf16 v[126:129], v[130:133], v[172:175], v[126:129]
	v_mfma_f32_16x16x32_bf16 v[122:125], v[138:141], v[172:175], v[122:125]
	v_mfma_f32_16x16x32_bf16 v[110:113], v[130:133], v[184:187], v[110:113]
	v_mfma_f32_16x16x32_bf16 v[106:109], v[138:141], v[184:187], v[106:109]
	v_mfma_f32_16x16x32_bf16 v[94:97], v[130:133], v[192:195], v[94:97]
	v_mfma_f32_16x16x32_bf16 v[90:93], v[138:141], v[192:195], v[90:93]
	v_mfma_f32_16x16x32_bf16 v[78:81], v[130:133], v[200:203], v[78:81]
	v_mfma_f32_16x16x32_bf16 v[74:77], v[138:141], v[200:203], v[74:77]
	v_mfma_f32_16x16x32_bf16 v[126:129], v[134:137], v[180:183], v[126:129]
	v_mfma_f32_16x16x32_bf16 v[122:125], v[142:145], v[180:183], v[122:125]
	v_mfma_f32_16x16x32_bf16 v[110:113], v[134:137], v[188:191], v[110:113]
	v_mfma_f32_16x16x32_bf16 v[106:109], v[142:145], v[188:191], v[106:109]
	v_mfma_f32_16x16x32_bf16 v[94:97], v[134:137], v[196:199], v[94:97]
	v_mfma_f32_16x16x32_bf16 v[90:93], v[142:145], v[196:199], v[90:93]
	v_mfma_f32_16x16x32_bf16 v[78:81], v[134:137], v[208:211], v[78:81]
	v_mfma_f32_16x16x32_bf16 v[74:77], v[142:145], v[208:211], v[74:77]
	v_mfma_f32_16x16x32_bf16 v[118:121], v[146:149], v[172:175], v[118:121]
	v_mfma_f32_16x16x32_bf16 v[114:117], v[164:167], v[172:175], v[114:117]
	v_mfma_f32_16x16x32_bf16 v[102:105], v[146:149], v[184:187], v[102:105]
	v_mfma_f32_16x16x32_bf16 v[98:101], v[164:167], v[184:187], v[98:101]
	v_mfma_f32_16x16x32_bf16 v[86:89], v[146:149], v[192:195], v[86:89]
	v_mfma_f32_16x16x32_bf16 v[82:85], v[164:167], v[192:195], v[82:85]
	v_mfma_f32_16x16x32_bf16 v[70:73], v[146:149], v[200:203], v[70:73]
	v_mfma_f32_16x16x32_bf16 v[66:69], v[164:167], v[200:203], v[66:69]
	v_mfma_f32_16x16x32_bf16 v[118:121], v[150:153], v[180:183], v[118:121]
	v_mfma_f32_16x16x32_bf16 v[114:117], v[168:171], v[180:183], v[114:117]
	v_mfma_f32_16x16x32_bf16 v[102:105], v[150:153], v[188:191], v[102:105]
	v_mfma_f32_16x16x32_bf16 v[98:101], v[168:171], v[188:191], v[98:101]
	v_mfma_f32_16x16x32_bf16 v[86:89], v[150:153], v[196:199], v[86:89]
	v_mfma_f32_16x16x32_bf16 v[82:85], v[168:171], v[196:199], v[82:85]
	v_mfma_f32_16x16x32_bf16 v[70:73], v[150:153], v[208:211], v[70:73]
	v_mfma_f32_16x16x32_bf16 v[66:69], v[168:171], v[208:211], v[66:69]
	s_setprio 0
	s_barrier
	s_add_i32 s84, s88, s6
	v_lshl_add_u64 v[204:205], s[80:81], 0, v[0:1]
	s_mov_b32 m0, s84
	ds_read_b128 v[172:175], v179 offset:16384
	ds_read_b128 v[180:183], v179 offset:17408
	ds_read_b128 v[184:187], v179 offset:18432
	ds_read_b128 v[188:191], v179 offset:19456
	ds_read_b128 v[192:195], v179 offset:20480
	ds_read_b128 v[196:199], v179 offset:21504
	ds_read_b128 v[200:203], v179 offset:22528
	ds_read_b128 v[208:211], v179 offset:23552
	global_load_lds_dwordx4 v[204:205], off
	s_add_i32 m0, s84, 0x2000
	s_add_u32 s84, s80, 0x80000
	v_lshl_add_u64 v[212:213], s[80:81], 0, v[158:159]
	s_addc_u32 s85, s81, 0
	s_add_i32 s86, s89, s6
	global_load_lds_dwordx4 v[212:213], off
	v_lshl_add_u64 v[230:231], s[84:85], 0, v[0:1]
	s_mov_b32 m0, s86
	v_lshl_add_u64 v[232:233], s[82:83], 0, v[156:157]
	global_load_lds_dwordx4 v[230:231], off
	s_add_i32 m0, s86, 0x2000
	v_lshl_add_u64 v[230:231], s[84:85], 0, v[158:159]
	global_load_lds_dwordx4 v[230:231], off
	s_mov_b32 m0, s7
	v_lshl_add_u64 v[230:231], s[82:83], 0, v[154:155]
	global_load_lds_dwordx4 v[230:231], off
	s_mov_b32 m0, s8
	s_nop 0
	global_load_lds_dwordx4 v[232:233], off
	s_waitcnt vmcnt(8)
	s_waitcnt lgkmcnt(0)
	s_barrier
	s_setprio 1
	v_mfma_f32_16x16x32_bf16 v[62:65], v[130:133], v[172:175], v[62:65]
	v_mfma_f32_16x16x32_bf16 v[58:61], v[138:141], v[172:175], v[58:61]
	v_mfma_f32_16x16x32_bf16 v[46:49], v[130:133], v[184:187], v[46:49]
	v_mfma_f32_16x16x32_bf16 v[42:45], v[138:141], v[184:187], v[42:45]
	v_mfma_f32_16x16x32_bf16 v[30:33], v[130:133], v[192:195], v[30:33]
	v_mfma_f32_16x16x32_bf16 v[26:29], v[138:141], v[192:195], v[26:29]
	v_mfma_f32_16x16x32_bf16 v[14:17], v[130:133], v[200:203], v[14:17]
	v_mfma_f32_16x16x32_bf16 v[10:13], v[138:141], v[200:203], v[10:13]
	v_mfma_f32_16x16x32_bf16 v[62:65], v[134:137], v[180:183], v[62:65]
	v_mfma_f32_16x16x32_bf16 v[58:61], v[142:145], v[180:183], v[58:61]
	v_mfma_f32_16x16x32_bf16 v[46:49], v[134:137], v[188:191], v[46:49]
	v_mfma_f32_16x16x32_bf16 v[42:45], v[142:145], v[188:191], v[42:45]
	v_mfma_f32_16x16x32_bf16 v[30:33], v[134:137], v[196:199], v[30:33]
	v_mfma_f32_16x16x32_bf16 v[26:29], v[142:145], v[196:199], v[26:29]
	v_mfma_f32_16x16x32_bf16 v[14:17], v[134:137], v[208:211], v[14:17]
	v_mfma_f32_16x16x32_bf16 v[10:13], v[142:145], v[208:211], v[10:13]
	v_mfma_f32_16x16x32_bf16 v[54:57], v[146:149], v[172:175], v[54:57]
	v_mfma_f32_16x16x32_bf16 v[50:53], v[164:167], v[172:175], v[50:53]
	v_mfma_f32_16x16x32_bf16 v[38:41], v[146:149], v[184:187], v[38:41]
	v_mfma_f32_16x16x32_bf16 v[34:37], v[164:167], v[184:187], v[34:37]
	v_mfma_f32_16x16x32_bf16 v[22:25], v[146:149], v[192:195], v[22:25]
	v_mfma_f32_16x16x32_bf16 v[18:21], v[164:167], v[192:195], v[18:21]
	v_mfma_f32_16x16x32_bf16 v[6:9], v[146:149], v[200:203], v[6:9]
	v_mfma_f32_16x16x32_bf16 v[2:5], v[164:167], v[200:203], v[2:5]
	v_mfma_f32_16x16x32_bf16 v[54:57], v[150:153], v[180:183], v[54:57]
	v_mfma_f32_16x16x32_bf16 v[50:53], v[168:171], v[180:183], v[50:53]
	v_mfma_f32_16x16x32_bf16 v[38:41], v[150:153], v[188:191], v[38:41]
	v_mfma_f32_16x16x32_bf16 v[34:37], v[168:171], v[188:191], v[34:37]
	v_mfma_f32_16x16x32_bf16 v[22:25], v[150:153], v[196:199], v[22:25]
	v_mfma_f32_16x16x32_bf16 v[18:21], v[168:171], v[196:199], v[18:21]
	v_mfma_f32_16x16x32_bf16 v[6:9], v[150:153], v[208:211], v[6:9]
	v_mfma_f32_16x16x32_bf16 v[2:5], v[168:171], v[208:211], v[2:5]
	s_setprio 0
	s_barrier
; #define PG8_STAGE(bufoff, gbase, voff) do { _Pragma("unroll") for (int _i = 0; _i < 2; ++_i) \
;         __builtin_amdgcn_global_load_lds((const unsigned*)((const char*)(gbase) + (voff)[_i]), (PG8_LAS unsigned*)(lds + (bufoff) + ldsw + _i * 8192), 16, 0, 0); } while (0)
; #define PG8_LDA(dst, b, h) do { _Pragma("unroll") for (int m = 0; m < 4; ++m) _Pragma("unroll") for (int k = 0; k < 2; ++k) dst[m][k] = *(const PG8_LAS bf16x8*)(lds + PG8_SA(b, h) + aoff + m * 2048 + k * 1024); } while (0)
; #define PG8_LDB(dst, b, h) do { _Pragma("unroll") for (int n = 0; n < 2; ++n) _Pragma("unroll") for (int k = 0; k < 2; ++k) dst[n][k] = *(const PG8_LAS bf16x8*)(lds + PG8_SB(b, h) + boff + n * 2048 + k * 1024); } while (0)
; #define PG8_MMA(ai, bj, At, Bt) do { __builtin_amdgcn_s_setprio(1); _Pragma("unroll") for (int m = 0; m < 4; ++m) _Pragma("unroll") for (int n = 0; n < 2; ++n) _Pragma("unroll") for (int k = 0; k < 2; ++k) \
;         acc[ai][bj][m][n] = __builtin_amdgcn_mfma_f32_16x16x32_bf16(Bt[n][k], At[m][k], acc[ai][bj][m][n], 0, 0, 0); __builtin_amdgcn_s_setprio(0); } while (0)
; #define PG8_WAIT_V(n) asm volatile("s_waitcnt vmcnt(" #n ")" ::: "memory")
; #define PG8_WAIT_L(n) asm volatile("s_waitcnt lgkmcnt(" #n ")" ::: "memory")
; #define PG8_BAR __builtin_amdgcn_s_barrier()
; #define PG8_SCHED __builtin_amdgcn_sched_barrier(0)
; template <class Epi, class Sched, bool ALIGN_EPI = false, bool SP2 = false>
; __device__ __forceinline__ void gemm_phase(PG8_LAS unsigned char* lds, const Gemm g, const Sched& S, const Epi& E) {
;     ...
;         for (int t = 0; t < nt; t += 2) {
;             const bool last = (t == nt - 2);
;             const char* a1 = cA + (size_t)(t + 1) * kstep;
;             const char* a2 = last ? nA : cA + (size_t)(t + 2) * kstep; const char* b2 = last ? nB : cB + (size_t)(t + 2) * kstep;
;     ...
;             PG8_LDB(B0, 1, 0); PG8_LDB(B1, 1, 1); PG8_SCHED; PG8_LDA(At, 1, 0); PG8_STAGE(PG8_SA(0, 1), a2 + hstep, voffA);
;             PG8_WAIT_V(8); PG8_WAIT_L(0); PG8_BAR; PG8_MMA(0, 0, At, B0); PG8_MMA(0, 1, At, B1); PG8_BAR; PG8_SCHED;
;             PG8_LDA(At, 1, 1); PG8_STAGE(PG8_SB(1, 0), b3, voffB); PG8_STAGE(PG8_SB(1, 1), b3 + hstep, voffB); PG8_STAGE(PG8_SA(1, 0), a3, voffA);
;             PG8_WAIT_V(8); PG8_WAIT_L(0); PG8_BAR; PG8_MMA(1, 0, At, B0); PG8_MMA(1, 1, At, B1); PG8_BAR; PG8_SCHED;
	s_add_i32 s84, 0, 0x1c000
	ds_read_b128 v[130:133], v244
	ds_read_b128 v[134:137], v244 offset:1024
	ds_read_b128 v[138:141], v244 offset:2048
	ds_read_b128 v[142:145], v244 offset:3072
	ds_read_b128 v[146:149], v245
	ds_read_b128 v[150:153], v245 offset:1024
	ds_read_b128 v[164:167], v245 offset:2048
	ds_read_b128 v[168:171], v245 offset:3072
	s_add_u32 s82, s82, 0x80000
	s_addc_u32 s83, s83, 0
	s_mov_b32 m0, s9
	v_lshl_add_u64 v[234:235], s[82:83], 0, v[154:155]
	ds_read_b128 v[172:175], v179 offset:32768
	ds_read_b128 v[180:183], v179 offset:33792
	ds_read_b128 v[184:187], v179 offset:34816
	ds_read_b128 v[188:191], v179 offset:35840
	ds_read_b128 v[192:195], v179 offset:36864
	ds_read_b128 v[196:199], v179 offset:37888
	ds_read_b128 v[200:203], v179 offset:38912
	ds_read_b128 v[208:211], v179 offset:39936
	global_load_lds_dwordx4 v[234:235], off
	s_mov_b32 m0, s10
	v_lshl_add_u64 v[234:235], s[82:83], 0, v[156:157]
	global_load_lds_dwordx4 v[234:235], off
	s_waitcnt vmcnt(8)
	s_waitcnt lgkmcnt(0)
	s_barrier
	s_setprio 1
	v_mfma_f32_16x16x32_bf16 v[126:129], v[130:133], v[172:175], v[126:129]
	v_mfma_f32_16x16x32_bf16 v[122:125], v[138:141], v[172:175], v[122:125]
	v_mfma_f32_16x16x32_bf16 v[110:113], v[130:133], v[184:187], v[110:113]
	v_mfma_f32_16x16x32_bf16 v[106:109], v[138:141], v[184:187], v[106:109]
	v_mfma_f32_16x16x32_bf16 v[94:97], v[130:133], v[192:195], v[94:97]
	v_mfma_f32_16x16x32_bf16 v[90:93], v[138:141], v[192:195], v[90:93]
	v_mfma_f32_16x16x32_bf16 v[78:81], v[130:133], v[200:203], v[78:81]
	v_mfma_f32_16x16x32_bf16 v[74:77], v[138:141], v[200:203], v[74:77]
	v_mfma_f32_16x16x32_bf16 v[126:129], v[134:137], v[180:183], v[126:129]
	v_mfma_f32_16x16x32_bf16 v[122:125], v[142:145], v[180:183], v[122:125]
	v_mfma_f32_16x16x32_bf16 v[110:113], v[134:137], v[188:191], v[110:113]
	v_mfma_f32_16x16x32_bf16 v[106:109], v[142:145], v[188:191], v[106:109]
	v_mfma_f32_16x16x32_bf16 v[94:97], v[134:137], v[196:199], v[94:97]
	v_mfma_f32_16x16x32_bf16 v[90:93], v[142:145], v[196:199], v[90:93]
	v_mfma_f32_16x16x32_bf16 v[78:81], v[134:137], v[208:211], v[78:81]
	v_mfma_f32_16x16x32_bf16 v[74:77], v[142:145], v[208:211], v[74:77]
	v_mfma_f32_16x16x32_bf16 v[118:121], v[146:149], v[172:175], v[118:121]
	v_mfma_f32_16x16x32_bf16 v[114:117], v[164:167], v[172:175], v[114:117]
	v_mfma_f32_16x16x32_bf16 v[102:105], v[146:149], v[184:187], v[102:105]
	v_mfma_f32_16x16x32_bf16 v[98:101], v[164:167], v[184:187], v[98:101]
	v_mfma_f32_16x16x32_bf16 v[86:89], v[146:149], v[192:195], v[86:89]
	v_mfma_f32_16x16x32_bf16 v[82:85], v[164:167], v[192:195], v[82:85]
	v_mfma_f32_16x16x32_bf16 v[70:73], v[146:149], v[200:203], v[70:73]
	v_mfma_f32_16x16x32_bf16 v[66:69], v[164:167], v[200:203], v[66:69]
	v_mfma_f32_16x16x32_bf16 v[118:121], v[150:153], v[180:183], v[118:121]
	v_mfma_f32_16x16x32_bf16 v[114:117], v[168:171], v[180:183], v[114:117]
	v_mfma_f32_16x16x32_bf16 v[102:105], v[150:153], v[188:191], v[102:105]
	v_mfma_f32_16x16x32_bf16 v[98:101], v[168:171], v[188:191], v[98:101]
	v_mfma_f32_16x16x32_bf16 v[86:89], v[150:153], v[196:199], v[86:89]
	v_mfma_f32_16x16x32_bf16 v[82:85], v[168:171], v[196:199], v[82:85]
	v_mfma_f32_16x16x32_bf16 v[70:73], v[150:153], v[208:211], v[70:73]
	v_mfma_f32_16x16x32_bf16 v[66:69], v[168:171], v[208:211], v[66:69]
	s_setprio 0
	s_barrier
	s_add_i32 s82, s90, s6
	v_lshl_add_u64 v[204:205], v[204:205], 0, s[70:71]
	s_mov_b32 m0, s82
	ds_read_b128 v[172:175], v179 offset:49152
	ds_read_b128 v[180:183], v179 offset:50176
	ds_read_b128 v[184:187], v179 offset:51200
	ds_read_b128 v[188:191], v179 offset:52224
	ds_read_b128 v[192:195], v179 offset:53248
	ds_read_b128 v[196:199], v179 offset:54272
	ds_read_b128 v[200:203], v179 offset:55296
	ds_read_b128 v[208:211], v179 offset:56320
	global_load_lds_dwordx4 v[204:205], off
	s_add_i32 m0, s82, 0x2000
	s_add_u32 s80, s80, 0x80080
	v_lshl_add_u64 v[204:205], v[212:213], 0, s[70:71]
	s_addc_u32 s81, s81, 0
	s_add_i32 s82, s84, s6
	global_load_lds_dwordx4 v[204:205], off
	s_mov_b32 m0, s82
	v_lshl_add_u64 v[204:205], s[80:81], 0, v[0:1]
	global_load_lds_dwordx4 v[204:205], off
	s_add_i32 m0, s82, 0x2000
	v_lshl_add_u64 v[204:205], s[80:81], 0, v[158:159]
	global_load_lds_dwordx4 v[204:205], off
	s_mov_b32 m0, s12
	v_lshl_add_u64 v[204:205], v[230:231], 0, s[70:71]
	global_load_lds_dwordx4 v[204:205], off
	s_mov_b32 m0, s13
	v_lshl_add_u64 v[204:205], v[232:233], 0, s[70:71]
	global_load_lds_dwordx4 v[204:205], off
	s_waitcnt vmcnt(8)
	s_waitcnt lgkmcnt(0)
	s_barrier
	s_setprio 1
	v_mfma_f32_16x16x32_bf16 v[62:65], v[130:133], v[172:175], v[62:65]
	v_mfma_f32_16x16x32_bf16 v[58:61], v[138:141], v[172:175], v[58:61]
	v_mfma_f32_16x16x32_bf16 v[46:49], v[130:133], v[184:187], v[46:49]
	v_mfma_f32_16x16x32_bf16 v[42:45], v[138:141], v[184:187], v[42:45]
	v_mfma_f32_16x16x32_bf16 v[30:33], v[130:133], v[192:195], v[30:33]
	v_mfma_f32_16x16x32_bf16 v[26:29], v[138:141], v[192:195], v[26:29]
	v_mfma_f32_16x16x32_bf16 v[14:17], v[130:133], v[200:203], v[14:17]
	v_mfma_f32_16x16x32_bf16 v[10:13], v[138:141], v[200:203], v[10:13]
	v_mfma_f32_16x16x32_bf16 v[62:65], v[134:137], v[180:183], v[62:65]
	v_mfma_f32_16x16x32_bf16 v[58:61], v[142:145], v[180:183], v[58:61]
	v_mfma_f32_16x16x32_bf16 v[46:49], v[134:137], v[188:191], v[46:49]
	v_mfma_f32_16x16x32_bf16 v[42:45], v[142:145], v[188:191], v[42:45]
	v_mfma_f32_16x16x32_bf16 v[30:33], v[134:137], v[196:199], v[30:33]
	v_mfma_f32_16x16x32_bf16 v[26:29], v[142:145], v[196:199], v[26:29]
	v_mfma_f32_16x16x32_bf16 v[14:17], v[134:137], v[208:211], v[14:17]
	v_mfma_f32_16x16x32_bf16 v[10:13], v[142:145], v[208:211], v[10:13]
	v_mfma_f32_16x16x32_bf16 v[54:57], v[146:149], v[172:175], v[54:57]
	v_mfma_f32_16x16x32_bf16 v[50:53], v[164:167], v[172:175], v[50:53]
	v_mfma_f32_16x16x32_bf16 v[38:41], v[146:149], v[184:187], v[38:41]
	v_mfma_f32_16x16x32_bf16 v[34:37], v[164:167], v[184:187], v[34:37]
	v_mfma_f32_16x16x32_bf16 v[22:25], v[146:149], v[192:195], v[22:25]
	v_mfma_f32_16x16x32_bf16 v[18:21], v[164:167], v[192:195], v[18:21]
	v_mfma_f32_16x16x32_bf16 v[6:9], v[146:149], v[200:203], v[6:9]
	v_mfma_f32_16x16x32_bf16 v[2:5], v[164:167], v[200:203], v[2:5]
	v_mfma_f32_16x16x32_bf16 v[54:57], v[150:153], v[180:183], v[54:57]
	v_mfma_f32_16x16x32_bf16 v[50:53], v[168:171], v[180:183], v[50:53]
	v_mfma_f32_16x16x32_bf16 v[38:41], v[150:153], v[188:191], v[38:41]
	v_mfma_f32_16x16x32_bf16 v[34:37], v[168:171], v[188:191], v[34:37]
	v_mfma_f32_16x16x32_bf16 v[22:25], v[150:153], v[196:199], v[22:25]
	v_mfma_f32_16x16x32_bf16 v[18:21], v[168:171], v[196:199], v[18:21]
	v_mfma_f32_16x16x32_bf16 v[6:9], v[150:153], v[208:211], v[6:9]
	v_mfma_f32_16x16x32_bf16 v[2:5], v[168:171], v[208:211], v[2:5]
	s_setprio 0
	s_add_i32 s52, s52, 2
	s_add_u32 s78, s78, 0x100
	s_addc_u32 s79, s79, 0
	s_add_u32 s47, s47, 0x100
	s_addc_u32 s51, s51, 0
	s_cmp_gt_u32 s52, 29
	s_barrier
	s_cbranch_scc0 .LBB0_180
	s_and_b64 vcc, exec, s[18:19]
	s_cbranch_vccz .LBB0_183
	s_barrier

; #define PG8_STAGE(bufoff, gbase, voff) do { _Pragma("unroll") for (int _i = 0; _i < 2; ++_i) \
;         __builtin_amdgcn_global_load_lds((const unsigned*)((const char*)(gbase) + (voff)[_i]), (PG8_LAS unsigned*)(lds + (bufoff) + ldsw + _i * 8192), 16, 0, 0); } while (0)
; #define PG8_LDA(dst, b, h) do { _Pragma("unroll") for (int m = 0; m < 4; ++m) _Pragma("unroll") for (int k = 0; k < 2; ++k) dst[m][k] = *(const PG8_LAS bf16x8*)(lds + PG8_SA(b, h) + aoff + m * 2048 + k * 1024); } while (0)
; #define PG8_LDB(dst, b, h) do { _Pragma("unroll") for (int n = 0; n < 2; ++n) _Pragma("unroll") for (int k = 0; k < 2; ++k) dst[n][k] = *(const PG8_LAS bf16x8*)(lds + PG8_SB(b, h) + boff + n * 2048 + k * 1024); } while (0)
; #define PG8_SCHED __builtin_amdgcn_sched_barrier(0)
; template <class Epi, class Sched, bool ALIGN_EPI = false, bool SP2 = false>
; __device__ __forceinline__ void gemm_phase(PG8_LAS unsigned char* lds, const Gemm g, const Sched& S, const Epi& E) {
;     ...
;     for (;;) {
;         const bool has_next = S.next(ui + 1, nxt);
;         const char* nA = has_next ? (const char*)g.A + (size_t)nxt.pm * tstep : cA; const char* nB = has_next ? (const char*)g.Bt + (size_t)nxt.pn * tstep : cB;
;         for (int t = 0; t < nt; t += 2) {
;             const bool last = (t == nt - 2);
;             const char* a1 = cA + (size_t)(t + 1) * kstep;
;             const char* a2 = last ? nA : cA + (size_t)(t + 2) * kstep; const char* b2 = last ? nB : cB + (size_t)(t + 2) * kstep;
;             const char* a3 = a2 + kstep; const char* b3 = b2 + kstep;
;             if (last && has_next) S.a_ready(nxt);
;             if constexpr (SP2) {
;             PG8_LDB(B0, 0, 0); PG8_LDB(B1, 0, 1); PG8_SCHED; PG8_LDA(At, 0, 0); PG8_STAGE(PG8_SA(1, 1), a1 + hstep, voffA);
;     ...
; #pragma unroll
;         for (int a = 0; a < 2; ++a)
; #pragma unroll
;             for (int b = 0; b < 2; ++b)
; #pragma unroll
;                 for (int m = 0; m < 4; ++m)
; #pragma unroll
;                     for (int n = 0; n < 2; ++n) acc[a][b][m][n] = (f32x4){0.f, 0.f, 0.f, 0.f};
;         cur = nxt; cA = nA; cB = nB; ++ui;
.Ltail_b:
	s_and_b64 s[34:35], s[38:39], exec
	s_cselect_b32 s17, s23, s41
	s_cselect_b32 s37, s22, s40
	s_add_u32 s34, s42, 0x80080
	s_addc_u32 s35, s43, 0
	s_add_u32 s44, s40, 0x100
	v_mov_b32_e32 v2, 0
	s_addc_u32 s45, s41, 0
	s_mov_b32 s46, -2
	v_mov_b32_e32 v3, v2
	v_mov_b32_e32 v4, v2
	v_mov_b32_e32 v5, v2
	v_mov_b32_e32 v6, v2
	v_mov_b32_e32 v7, v2
	v_mov_b32_e32 v8, v2
	v_mov_b32_e32 v9, v2
	v_mov_b32_e32 v18, v2
	v_mov_b32_e32 v19, v2
	v_mov_b32_e32 v20, v2
	v_mov_b32_e32 v21, v2
	v_mov_b32_e32 v22, v2
	v_mov_b32_e32 v23, v2
	v_mov_b32_e32 v24, v2
	v_mov_b32_e32 v25, v2
	v_mov_b32_e32 v34, v2
	v_mov_b32_e32 v35, v2
	v_mov_b32_e32 v36, v2
	v_mov_b32_e32 v37, v2
	v_mov_b32_e32 v38, v2
	v_mov_b32_e32 v39, v2
	v_mov_b32_e32 v40, v2
	v_mov_b32_e32 v41, v2
	v_mov_b32_e32 v50, v2
	v_mov_b32_e32 v51, v2
	v_mov_b32_e32 v52, v2
	v_mov_b32_e32 v53, v2
	v_mov_b32_e32 v54, v2
	v_mov_b32_e32 v55, v2
	v_mov_b32_e32 v56, v2
	v_mov_b32_e32 v57, v2
	v_mov_b32_e32 v10, v2
	v_mov_b32_e32 v11, v2
	v_mov_b32_e32 v12, v2
	v_mov_b32_e32 v13, v2
	v_mov_b32_e32 v14, v2
	v_mov_b32_e32 v15, v2
	v_mov_b32_e32 v16, v2
	v_mov_b32_e32 v17, v2
	v_mov_b32_e32 v26, v2
	v_mov_b32_e32 v27, v2
	v_mov_b32_e32 v28, v2
	v_mov_b32_e32 v29, v2
	v_mov_b32_e32 v30, v2
	v_mov_b32_e32 v31, v2
	v_mov_b32_e32 v32, v2
	v_mov_b32_e32 v33, v2
	v_mov_b32_e32 v42, v2
	v_mov_b32_e32 v43, v2
	v_mov_b32_e32 v44, v2
	v_mov_b32_e32 v45, v2
	v_mov_b32_e32 v46, v2
	v_mov_b32_e32 v47, v2
	v_mov_b32_e32 v48, v2
	v_mov_b32_e32 v49, v2
	v_mov_b32_e32 v58, v2
	v_mov_b32_e32 v59, v2
	v_mov_b32_e32 v60, v2
	v_mov_b32_e32 v61, v2
	v_mov_b32_e32 v62, v2
	v_mov_b32_e32 v63, v2
	v_mov_b32_e32 v64, v2
	v_mov_b32_e32 v65, v2
	v_mov_b32_e32 v66, v2
	v_mov_b32_e32 v67, v2
	v_mov_b32_e32 v68, v2
	v_mov_b32_e32 v69, v2
	v_mov_b32_e32 v70, v2
	v_mov_b32_e32 v71, v2
	v_mov_b32_e32 v72, v2
	v_mov_b32_e32 v73, v2
	v_mov_b32_e32 v82, v2
	v_mov_b32_e32 v83, v2
	v_mov_b32_e32 v84, v2
	v_mov_b32_e32 v85, v2
	v_mov_b32_e32 v86, v2
	v_mov_b32_e32 v87, v2
	v_mov_b32_e32 v88, v2
	v_mov_b32_e32 v89, v2
	v_mov_b32_e32 v98, v2
	v_mov_b32_e32 v99, v2
	v_mov_b32_e32 v100, v2
	v_mov_b32_e32 v101, v2
	v_mov_b32_e32 v102, v2
	v_mov_b32_e32 v103, v2
	v_mov_b32_e32 v104, v2
	v_mov_b32_e32 v105, v2
	v_mov_b32_e32 v122, v2
	v_mov_b32_e32 v123, v2
	v_mov_b32_e32 v124, v2
	v_mov_b32_e32 v125, v2
	v_mov_b32_e32 v126, v2
	v_mov_b32_e32 v127, v2
	v_mov_b32_e32 v128, v2
	v_mov_b32_e32 v129, v2
	v_mov_b32_e32 v74, v2
	v_mov_b32_e32 v75, v2
	v_mov_b32_e32 v76, v2
	v_mov_b32_e32 v77, v2
	v_mov_b32_e32 v78, v2
	v_mov_b32_e32 v79, v2
	v_mov_b32_e32 v80, v2
	v_mov_b32_e32 v81, v2
	v_mov_b32_e32 v90, v2
	v_mov_b32_e32 v91, v2
	v_mov_b32_e32 v92, v2
	v_mov_b32_e32 v93, v2
	v_mov_b32_e32 v94, v2
	v_mov_b32_e32 v95, v2
	v_mov_b32_e32 v96, v2
	v_mov_b32_e32 v97, v2
	v_mov_b32_e32 v106, v2
	v_mov_b32_e32 v107, v2
	v_mov_b32_e32 v108, v2
	v_mov_b32_e32 v109, v2
	v_mov_b32_e32 v110, v2
	v_mov_b32_e32 v111, v2
	v_mov_b32_e32 v112, v2
	v_mov_b32_e32 v113, v2
	v_mov_b32_e32 v138, v2
	v_mov_b32_e32 v139, v2
	v_mov_b32_e32 v140, v2
	v_mov_b32_e32 v141, v2
	v_mov_b32_e32 v142, v2
	v_mov_b32_e32 v143, v2
	v_mov_b32_e32 v144, v2
	v_mov_b32_e32 v145, v2
	v_add_u32_e32 v242, s88, v177
	v_add_u32_e32 v243, s89, v177
	v_add_u32_e32 v244, s90, v177
	v_add_u32_e32 v245, 0x1c000, v177
	s_cmp_eq_u32 s27, s85
	s_cbranch_scc1 .Ltail_loop
.LBB0_214:
	ds_read_b128 v[114:117], v242
	ds_read_b128 v[118:121], v242 offset:1024
	ds_read_b128 v[130:133], v242 offset:2048
	ds_read_b128 v[134:137], v242 offset:3072
	ds_read_b128 v[146:149], v243
	ds_read_b128 v[150:153], v243 offset:1024
	ds_read_b128 v[168:171], v243 offset:2048
	ds_read_b128 v[172:175], v243 offset:3072
	s_add_u32 s40, s34, 0xfff80080
	s_addc_u32 s41, s35, -1
	s_cmp_eq_u32 s46, 28
	s_cselect_b32 s43, s15, s41
	s_cselect_b32 s42, s19, s40
	s_cselect_b32 s41, s17, s45
	s_cselect_b32 s40, s37, s44
	v_lshl_add_u64 v[204:205], s[34:35], 0, v[164:165]
	s_add_i32 m0, s8, 0xc000
	ds_read_b128 v[180:183], v178
	ds_read_b128 v[184:187], v178 offset:1024
	ds_read_b128 v[188:191], v178 offset:2048
	ds_read_b128 v[192:195], v178 offset:3072
	ds_read_b128 v[196:199], v178 offset:4096
	ds_read_b128 v[200:203], v178 offset:5120
	ds_read_b128 v[208:211], v178 offset:6144
	ds_read_b128 v[230:233], v178 offset:7168
	global_load_lds_dwordx4 v[204:205], off
	s_add_i32 m0, s8, 0xe000
	v_lshl_add_u64 v[204:205], s[34:35], 0, v[166:167]
	global_load_lds_dwordx4 v[204:205], off
	s_waitcnt vmcnt(8)
	s_waitcnt lgkmcnt(0)
	s_barrier
; #define PG8_STAGE(bufoff, gbase, voff) do { _Pragma("unroll") for (int _i = 0; _i < 2; ++_i) \
;         __builtin_amdgcn_global_load_lds((const unsigned*)((const char*)(gbase) + (voff)[_i]), (PG8_LAS unsigned*)(lds + (bufoff) + ldsw + _i * 8192), 16, 0, 0); } while (0)
; #define PG8_LDA(dst, b, h) do { _Pragma("unroll") for (int m = 0; m < 4; ++m) _Pragma("unroll") for (int k = 0; k < 2; ++k) dst[m][k] = *(const PG8_LAS bf16x8*)(lds + PG8_SA(b, h) + aoff + m * 2048 + k * 1024); } while (0)
; #define PG8_LDB(dst, b, h) do { _Pragma("unroll") for (int n = 0; n < 2; ++n) _Pragma("unroll") for (int k = 0; k < 2; ++k) dst[n][k] = *(const PG8_LAS bf16x8*)(lds + PG8_SB(b, h) + boff + n * 2048 + k * 1024); } while (0)
; #define PG8_MMA(ai, bj, At, Bt) do { __builtin_amdgcn_s_setprio(1); _Pragma("unroll") for (int m = 0; m < 4; ++m) _Pragma("unroll") for (int n = 0; n < 2; ++n) _Pragma("unroll") for (int k = 0; k < 2; ++k) \
;         acc[ai][bj][m][n] = __builtin_amdgcn_mfma_f32_16x16x32_bf16(Bt[n][k], At[m][k], acc[ai][bj][m][n], 0, 0, 0); __builtin_amdgcn_s_setprio(0); } while (0)
; #define PG8_WAIT_V(n) asm volatile("s_waitcnt vmcnt(" #n ")" ::: "memory")
; #define PG8_WAIT_L(n) asm volatile("s_waitcnt lgkmcnt(" #n ")" ::: "memory")
; #define PG8_BAR __builtin_amdgcn_s_barrier()
; #define PG8_SCHED __builtin_amdgcn_sched_barrier(0)
; template <class Epi, class Sched, bool ALIGN_EPI = false, bool SP2 = false>
; __device__ __forceinline__ void gemm_phase(PG8_LAS unsigned char* lds, const Gemm g, const Sched& S, const Epi& E) {
;     ...
;             PG8_LDB(B0, 0, 0); PG8_LDB(B1, 0, 1); PG8_SCHED; PG8_LDA(At, 0, 0); PG8_STAGE(PG8_SA(1, 1), a1 + hstep, voffA);
;             PG8_WAIT_V(8); PG8_WAIT_L(0); PG8_BAR; PG8_MMA(0, 0, At, B0); PG8_MMA(0, 1, At, B1); PG8_BAR; PG8_SCHED;
;             PG8_LDA(At, 0, 1); PG8_STAGE(PG8_SB(0, 0), b2, voffB); PG8_STAGE(PG8_SB(0, 1), b2 + hstep, voffB); PG8_STAGE(PG8_SA(0, 0), a2, voffA);
;             PG8_WAIT_V(8); PG8_WAIT_L(0); PG8_BAR; PG8_MMA(1, 0, At, B0); PG8_MMA(1, 1, At, B1); PG8_BAR; PG8_SCHED;
	s_setprio 1
	v_mfma_f32_16x16x32_bf16 v[142:145], v[114:117], v[180:183], v[142:145]
	v_mfma_f32_16x16x32_bf16 v[138:141], v[130:133], v[180:183], v[138:141]
	v_mfma_f32_16x16x32_bf16 v[110:113], v[114:117], v[188:191], v[110:113]
	v_mfma_f32_16x16x32_bf16 v[106:109], v[130:133], v[188:191], v[106:109]
	v_mfma_f32_16x16x32_bf16 v[94:97], v[114:117], v[196:199], v[94:97]
	v_mfma_f32_16x16x32_bf16 v[90:93], v[130:133], v[196:199], v[90:93]
	v_mfma_f32_16x16x32_bf16 v[78:81], v[114:117], v[208:211], v[78:81]
	v_mfma_f32_16x16x32_bf16 v[74:77], v[130:133], v[208:211], v[74:77]
	v_mfma_f32_16x16x32_bf16 v[142:145], v[118:121], v[184:187], v[142:145]
	v_mfma_f32_16x16x32_bf16 v[138:141], v[134:137], v[184:187], v[138:141]
	v_mfma_f32_16x16x32_bf16 v[110:113], v[118:121], v[192:195], v[110:113]
	v_mfma_f32_16x16x32_bf16 v[106:109], v[134:137], v[192:195], v[106:109]
	v_mfma_f32_16x16x32_bf16 v[94:97], v[118:121], v[200:203], v[94:97]
	v_mfma_f32_16x16x32_bf16 v[90:93], v[134:137], v[200:203], v[90:93]
	v_mfma_f32_16x16x32_bf16 v[78:81], v[118:121], v[230:233], v[78:81]
	v_mfma_f32_16x16x32_bf16 v[74:77], v[134:137], v[230:233], v[74:77]
	v_mfma_f32_16x16x32_bf16 v[126:129], v[146:149], v[180:183], v[126:129]
	v_mfma_f32_16x16x32_bf16 v[122:125], v[168:171], v[180:183], v[122:125]
	v_mfma_f32_16x16x32_bf16 v[102:105], v[146:149], v[188:191], v[102:105]
	v_mfma_f32_16x16x32_bf16 v[98:101], v[168:171], v[188:191], v[98:101]
	v_mfma_f32_16x16x32_bf16 v[86:89], v[146:149], v[196:199], v[86:89]
	v_mfma_f32_16x16x32_bf16 v[82:85], v[168:171], v[196:199], v[82:85]
	v_mfma_f32_16x16x32_bf16 v[70:73], v[146:149], v[208:211], v[70:73]
	v_mfma_f32_16x16x32_bf16 v[66:69], v[168:171], v[208:211], v[66:69]
	v_mfma_f32_16x16x32_bf16 v[126:129], v[150:153], v[184:187], v[126:129]
	v_mfma_f32_16x16x32_bf16 v[122:125], v[172:175], v[184:187], v[122:125]
	v_mfma_f32_16x16x32_bf16 v[102:105], v[150:153], v[192:195], v[102:105]
	v_mfma_f32_16x16x32_bf16 v[98:101], v[172:175], v[192:195], v[98:101]
	v_mfma_f32_16x16x32_bf16 v[86:89], v[150:153], v[200:203], v[86:89]
	v_mfma_f32_16x16x32_bf16 v[82:85], v[172:175], v[200:203], v[82:85]
	v_mfma_f32_16x16x32_bf16 v[70:73], v[150:153], v[230:233], v[70:73]
	v_mfma_f32_16x16x32_bf16 v[66:69], v[172:175], v[230:233], v[66:69]
	s_setprio 0
	s_barrier
	s_add_i32 s47, s88, s6
	v_lshl_add_u64 v[204:205], s[40:41], 0, v[0:1]
	s_mov_b32 m0, s47
	ds_read_b128 v[180:183], v178 offset:16384
	ds_read_b128 v[184:187], v178 offset:17408
	ds_read_b128 v[188:191], v178 offset:18432
	ds_read_b128 v[192:195], v178 offset:19456
	ds_read_b128 v[196:199], v178 offset:20480
	ds_read_b128 v[200:203], v178 offset:21504
	ds_read_b128 v[208:211], v178 offset:22528
	ds_read_b128 v[230:233], v178 offset:23552
	global_load_lds_dwordx4 v[204:205], off
	s_add_i32 m0, s47, 0x2000
	s_add_u32 s50, s40, 0x80000
	v_lshl_add_u64 v[212:213], s[40:41], 0, v[154:155]
	s_addc_u32 s51, s41, 0
	s_add_i32 s47, s89, s6
	global_load_lds_dwordx4 v[212:213], off
	v_lshl_add_u64 v[234:235], s[50:51], 0, v[0:1]
	s_mov_b32 m0, s47
	v_lshl_add_u64 v[236:237], s[42:43], 0, v[156:157]
	global_load_lds_dwordx4 v[234:235], off
	s_add_i32 m0, s47, 0x2000
	v_lshl_add_u64 v[234:235], s[50:51], 0, v[154:155]
	global_load_lds_dwordx4 v[234:235], off
	s_mov_b32 m0, s8
	v_lshl_add_u64 v[234:235], s[42:43], 0, v[158:159]
	global_load_lds_dwordx4 v[234:235], off
	s_mov_b32 m0, s9
	s_nop 0
	global_load_lds_dwordx4 v[236:237], off
	s_waitcnt vmcnt(8)
	s_waitcnt lgkmcnt(0)
	s_barrier
	s_setprio 1
	v_mfma_f32_16x16x32_bf16 v[62:65], v[114:117], v[180:183], v[62:65]
	v_mfma_f32_16x16x32_bf16 v[58:61], v[130:133], v[180:183], v[58:61]
	v_mfma_f32_16x16x32_bf16 v[46:49], v[114:117], v[188:191], v[46:49]
	v_mfma_f32_16x16x32_bf16 v[42:45], v[130:133], v[188:191], v[42:45]
	v_mfma_f32_16x16x32_bf16 v[30:33], v[114:117], v[196:199], v[30:33]
	v_mfma_f32_16x16x32_bf16 v[26:29], v[130:133], v[196:199], v[26:29]
	v_mfma_f32_16x16x32_bf16 v[14:17], v[114:117], v[208:211], v[14:17]
	v_mfma_f32_16x16x32_bf16 v[10:13], v[130:133], v[208:211], v[10:13]
	v_mfma_f32_16x16x32_bf16 v[62:65], v[118:121], v[184:187], v[62:65]
	v_mfma_f32_16x16x32_bf16 v[58:61], v[134:137], v[184:187], v[58:61]
	v_mfma_f32_16x16x32_bf16 v[46:49], v[118:121], v[192:195], v[46:49]
	v_mfma_f32_16x16x32_bf16 v[42:45], v[134:137], v[192:195], v[42:45]
	v_mfma_f32_16x16x32_bf16 v[30:33], v[118:121], v[200:203], v[30:33]
	v_mfma_f32_16x16x32_bf16 v[26:29], v[134:137], v[200:203], v[26:29]
	v_mfma_f32_16x16x32_bf16 v[14:17], v[118:121], v[230:233], v[14:17]
	v_mfma_f32_16x16x32_bf16 v[10:13], v[134:137], v[230:233], v[10:13]
	v_mfma_f32_16x16x32_bf16 v[54:57], v[146:149], v[180:183], v[54:57]
	v_mfma_f32_16x16x32_bf16 v[50:53], v[168:171], v[180:183], v[50:53]
	v_mfma_f32_16x16x32_bf16 v[38:41], v[146:149], v[188:191], v[38:41]
	v_mfma_f32_16x16x32_bf16 v[34:37], v[168:171], v[188:191], v[34:37]
	v_mfma_f32_16x16x32_bf16 v[22:25], v[146:149], v[196:199], v[22:25]
	v_mfma_f32_16x16x32_bf16 v[18:21], v[168:171], v[196:199], v[18:21]
	v_mfma_f32_16x16x32_bf16 v[6:9], v[146:149], v[208:211], v[6:9]
	v_mfma_f32_16x16x32_bf16 v[2:5], v[168:171], v[208:211], v[2:5]
	v_mfma_f32_16x16x32_bf16 v[54:57], v[150:153], v[184:187], v[54:57]
	v_mfma_f32_16x16x32_bf16 v[50:53], v[172:175], v[184:187], v[50:53]
	v_mfma_f32_16x16x32_bf16 v[38:41], v[150:153], v[192:195], v[38:41]
	v_mfma_f32_16x16x32_bf16 v[34:37], v[172:175], v[192:195], v[34:37]
	v_mfma_f32_16x16x32_bf16 v[22:25], v[150:153], v[200:203], v[22:25]
	v_mfma_f32_16x16x32_bf16 v[18:21], v[172:175], v[200:203], v[18:21]
	v_mfma_f32_16x16x32_bf16 v[6:9], v[150:153], v[230:233], v[6:9]
	v_mfma_f32_16x16x32_bf16 v[2:5], v[172:175], v[230:233], v[2:5]
	s_setprio 0
	s_barrier
; #define PG8_STAGE(bufoff, gbase, voff) do { _Pragma("unroll") for (int _i = 0; _i < 2; ++_i) \
;         __builtin_amdgcn_global_load_lds((const unsigned*)((const char*)(gbase) + (voff)[_i]), (PG8_LAS unsigned*)(lds + (bufoff) + ldsw + _i * 8192), 16, 0, 0); } while (0)
; #define PG8_LDA(dst, b, h) do { _Pragma("unroll") for (int m = 0; m < 4; ++m) _Pragma("unroll") for (int k = 0; k < 2; ++k) dst[m][k] = *(const PG8_LAS bf16x8*)(lds + PG8_SA(b, h) + aoff + m * 2048 + k * 1024); } while (0)
; #define PG8_LDB(dst, b, h) do { _Pragma("unroll") for (int n = 0; n < 2; ++n) _Pragma("unroll") for (int k = 0; k < 2; ++k) dst[n][k] = *(const PG8_LAS bf16x8*)(lds + PG8_SB(b, h) + boff + n * 2048 + k * 1024); } while (0)
; #define PG8_MMA(ai, bj, At, Bt) do { __builtin_amdgcn_s_setprio(1); _Pragma("unroll") for (int m = 0; m < 4; ++m) _Pragma("unroll") for (int n = 0; n < 2; ++n) _Pragma("unroll") for (int k = 0; k < 2; ++k) \
;         acc[ai][bj][m][n] = __builtin_amdgcn_mfma_f32_16x16x32_bf16(Bt[n][k], At[m][k], acc[ai][bj][m][n], 0, 0, 0); __builtin_amdgcn_s_setprio(0); } while (0)
; #define PG8_WAIT_V(n) asm volatile("s_waitcnt vmcnt(" #n ")" ::: "memory")
; #define PG8_WAIT_L(n) asm volatile("s_waitcnt lgkmcnt(" #n ")" ::: "memory")
; #define PG8_BAR __builtin_amdgcn_s_barrier()
; #define PG8_SCHED __builtin_amdgcn_sched_barrier(0)
; template <class Epi, class Sched, bool ALIGN_EPI = false, bool SP2 = false>
; __device__ __forceinline__ void gemm_phase(PG8_LAS unsigned char* lds, const Gemm g, const Sched& S, const Epi& E) {
;     ...
;         for (int t = 0; t < nt; t += 2) {
;             const bool last = (t == nt - 2);
;             const char* a1 = cA + (size_t)(t + 1) * kstep;
;             const char* a2 = last ? nA : cA + (size_t)(t + 2) * kstep; const char* b2 = last ? nB : cB + (size_t)(t + 2) * kstep;
;     ...
;             PG8_LDB(B0, 1, 0); PG8_LDB(B1, 1, 1); PG8_SCHED; PG8_LDA(At, 1, 0); PG8_STAGE(PG8_SA(0, 1), a2 + hstep, voffA);
;             PG8_WAIT_V(8); PG8_WAIT_L(0); PG8_BAR; PG8_MMA(0, 0, At, B0); PG8_MMA(0, 1, At, B1); PG8_BAR; PG8_SCHED;
;             PG8_LDA(At, 1, 1); PG8_STAGE(PG8_SB(1, 0), b3, voffB); PG8_STAGE(PG8_SB(1, 1), b3 + hstep, voffB); PG8_STAGE(PG8_SA(1, 0), a3, voffA);
;             PG8_WAIT_V(8); PG8_WAIT_L(0); PG8_BAR; PG8_MMA(1, 0, At, B0); PG8_MMA(1, 1, At, B1); PG8_BAR; PG8_SCHED;
	s_add_i32 s47, 0, 0x1c000
	ds_read_b128 v[114:117], v244
	ds_read_b128 v[118:121], v244 offset:1024
	ds_read_b128 v[130:133], v244 offset:2048
	ds_read_b128 v[134:137], v244 offset:3072
	ds_read_b128 v[146:149], v245
	ds_read_b128 v[150:153], v245 offset:1024
	ds_read_b128 v[168:171], v245 offset:2048
	ds_read_b128 v[172:175], v245 offset:3072
	s_add_u32 s42, s42, 0x80000
	s_addc_u32 s43, s43, 0
	s_mov_b32 m0, s10
	v_lshl_add_u64 v[238:239], s[42:43], 0, v[158:159]
	ds_read_b128 v[180:183], v178 offset:32768
	ds_read_b128 v[184:187], v178 offset:33792
	ds_read_b128 v[188:191], v178 offset:34816
	ds_read_b128 v[192:195], v178 offset:35840
	ds_read_b128 v[196:199], v178 offset:36864
	ds_read_b128 v[200:203], v178 offset:37888
	ds_read_b128 v[208:211], v178 offset:38912
	ds_read_b128 v[230:233], v178 offset:39936
	global_load_lds_dwordx4 v[238:239], off
	s_mov_b32 m0, s11
	v_lshl_add_u64 v[238:239], s[42:43], 0, v[156:157]
	global_load_lds_dwordx4 v[238:239], off
	s_waitcnt vmcnt(8)
	s_waitcnt lgkmcnt(0)
	s_barrier
	s_setprio 1
	v_mfma_f32_16x16x32_bf16 v[142:145], v[114:117], v[180:183], v[142:145]
	v_mfma_f32_16x16x32_bf16 v[138:141], v[130:133], v[180:183], v[138:141]
	v_mfma_f32_16x16x32_bf16 v[110:113], v[114:117], v[188:191], v[110:113]
	v_mfma_f32_16x16x32_bf16 v[106:109], v[130:133], v[188:191], v[106:109]
	v_mfma_f32_16x16x32_bf16 v[94:97], v[114:117], v[196:199], v[94:97]
	v_mfma_f32_16x16x32_bf16 v[90:93], v[130:133], v[196:199], v[90:93]
	v_mfma_f32_16x16x32_bf16 v[78:81], v[114:117], v[208:211], v[78:81]
	v_mfma_f32_16x16x32_bf16 v[74:77], v[130:133], v[208:211], v[74:77]
	v_mfma_f32_16x16x32_bf16 v[142:145], v[118:121], v[184:187], v[142:145]
	v_mfma_f32_16x16x32_bf16 v[138:141], v[134:137], v[184:187], v[138:141]
	v_mfma_f32_16x16x32_bf16 v[110:113], v[118:121], v[192:195], v[110:113]
	v_mfma_f32_16x16x32_bf16 v[106:109], v[134:137], v[192:195], v[106:109]
	v_mfma_f32_16x16x32_bf16 v[94:97], v[118:121], v[200:203], v[94:97]
	v_mfma_f32_16x16x32_bf16 v[90:93], v[134:137], v[200:203], v[90:93]
	v_mfma_f32_16x16x32_bf16 v[78:81], v[118:121], v[230:233], v[78:81]
	v_mfma_f32_16x16x32_bf16 v[74:77], v[134:137], v[230:233], v[74:77]
	v_mfma_f32_16x16x32_bf16 v[126:129], v[146:149], v[180:183], v[126:129]
	v_mfma_f32_16x16x32_bf16 v[122:125], v[168:171], v[180:183], v[122:125]
	v_mfma_f32_16x16x32_bf16 v[102:105], v[146:149], v[188:191], v[102:105]
	v_mfma_f32_16x16x32_bf16 v[98:101], v[168:171], v[188:191], v[98:101]
	v_mfma_f32_16x16x32_bf16 v[86:89], v[146:149], v[196:199], v[86:89]
	v_mfma_f32_16x16x32_bf16 v[82:85], v[168:171], v[196:199], v[82:85]
	v_mfma_f32_16x16x32_bf16 v[70:73], v[146:149], v[208:211], v[70:73]
	v_mfma_f32_16x16x32_bf16 v[66:69], v[168:171], v[208:211], v[66:69]
	v_mfma_f32_16x16x32_bf16 v[126:129], v[150:153], v[184:187], v[126:129]
	v_mfma_f32_16x16x32_bf16 v[122:125], v[172:175], v[184:187], v[122:125]
	v_mfma_f32_16x16x32_bf16 v[102:105], v[150:153], v[192:195], v[102:105]
	v_mfma_f32_16x16x32_bf16 v[98:101], v[172:175], v[192:195], v[98:101]
	v_mfma_f32_16x16x32_bf16 v[86:89], v[150:153], v[200:203], v[86:89]
	v_mfma_f32_16x16x32_bf16 v[82:85], v[172:175], v[200:203], v[82:85]
	v_mfma_f32_16x16x32_bf16 v[70:73], v[150:153], v[230:233], v[70:73]
	v_mfma_f32_16x16x32_bf16 v[66:69], v[172:175], v[230:233], v[66:69]
	s_setprio 0
	s_barrier
	s_add_i32 s42, s90, s6
	v_lshl_add_u64 v[204:205], v[204:205], 0, s[70:71]
	s_mov_b32 m0, s42
	ds_read_b128 v[180:183], v178 offset:49152
	ds_read_b128 v[184:187], v178 offset:50176
	ds_read_b128 v[188:191], v178 offset:51200
	ds_read_b128 v[192:195], v178 offset:52224
	ds_read_b128 v[196:199], v178 offset:53248
	ds_read_b128 v[200:203], v178 offset:54272
	ds_read_b128 v[208:211], v178 offset:55296
	ds_read_b128 v[230:233], v178 offset:56320
	global_load_lds_dwordx4 v[204:205], off
	s_add_i32 m0, s42, 0x2000
	s_add_u32 s40, s40, 0x80080
	v_lshl_add_u64 v[204:205], v[212:213], 0, s[70:71]
	s_addc_u32 s41, s41, 0
	s_add_i32 s42, s47, s6
	global_load_lds_dwordx4 v[204:205], off
	s_mov_b32 m0, s42
	v_lshl_add_u64 v[204:205], s[40:41], 0, v[0:1]
	global_load_lds_dwordx4 v[204:205], off
	s_add_i32 m0, s42, 0x2000
	v_lshl_add_u64 v[204:205], s[40:41], 0, v[154:155]
	global_load_lds_dwordx4 v[204:205], off
	s_mov_b32 m0, s13
	v_lshl_add_u64 v[204:205], v[234:235], 0, s[70:71]
	global_load_lds_dwordx4 v[204:205], off
	s_mov_b32 m0, s25
	v_lshl_add_u64 v[204:205], v[236:237], 0, s[70:71]
	global_load_lds_dwordx4 v[204:205], off
	s_waitcnt vmcnt(8)
	s_waitcnt lgkmcnt(0)
	s_barrier
	s_setprio 1
	v_mfma_f32_16x16x32_bf16 v[62:65], v[114:117], v[180:183], v[62:65]
	v_mfma_f32_16x16x32_bf16 v[58:61], v[130:133], v[180:183], v[58:61]
	v_mfma_f32_16x16x32_bf16 v[46:49], v[114:117], v[188:191], v[46:49]
	v_mfma_f32_16x16x32_bf16 v[42:45], v[130:133], v[188:191], v[42:45]
	v_mfma_f32_16x16x32_bf16 v[30:33], v[114:117], v[196:199], v[30:33]
	v_mfma_f32_16x16x32_bf16 v[26:29], v[130:133], v[196:199], v[26:29]
	v_mfma_f32_16x16x32_bf16 v[14:17], v[114:117], v[208:211], v[14:17]
	v_mfma_f32_16x16x32_bf16 v[10:13], v[130:133], v[208:211], v[10:13]
	v_mfma_f32_16x16x32_bf16 v[62:65], v[118:121], v[184:187], v[62:65]
	v_mfma_f32_16x16x32_bf16 v[58:61], v[134:137], v[184:187], v[58:61]
	v_mfma_f32_16x16x32_bf16 v[46:49], v[118:121], v[192:195], v[46:49]
	v_mfma_f32_16x16x32_bf16 v[42:45], v[134:137], v[192:195], v[42:45]
	v_mfma_f32_16x16x32_bf16 v[30:33], v[118:121], v[200:203], v[30:33]
	v_mfma_f32_16x16x32_bf16 v[26:29], v[134:137], v[200:203], v[26:29]
	v_mfma_f32_16x16x32_bf16 v[14:17], v[118:121], v[230:233], v[14:17]
	v_mfma_f32_16x16x32_bf16 v[10:13], v[134:137], v[230:233], v[10:13]
	v_mfma_f32_16x16x32_bf16 v[54:57], v[146:149], v[180:183], v[54:57]
	v_mfma_f32_16x16x32_bf16 v[50:53], v[168:171], v[180:183], v[50:53]
	v_mfma_f32_16x16x32_bf16 v[38:41], v[146:149], v[188:191], v[38:41]
	v_mfma_f32_16x16x32_bf16 v[34:37], v[168:171], v[188:191], v[34:37]
	v_mfma_f32_16x16x32_bf16 v[22:25], v[146:149], v[196:199], v[22:25]
	v_mfma_f32_16x16x32_bf16 v[18:21], v[168:171], v[196:199], v[18:21]
	v_mfma_f32_16x16x32_bf16 v[6:9], v[146:149], v[208:211], v[6:9]
	v_mfma_f32_16x16x32_bf16 v[2:5], v[168:171], v[208:211], v[2:5]
	v_mfma_f32_16x16x32_bf16 v[54:57], v[150:153], v[184:187], v[54:57]
	v_mfma_f32_16x16x32_bf16 v[50:53], v[172:175], v[184:187], v[50:53]
	v_mfma_f32_16x16x32_bf16 v[38:41], v[150:153], v[192:195], v[38:41]
	v_mfma_f32_16x16x32_bf16 v[34:37], v[172:175], v[192:195], v[34:37]
	v_mfma_f32_16x16x32_bf16 v[22:25], v[150:153], v[200:203], v[22:25]
	v_mfma_f32_16x16x32_bf16 v[18:21], v[172:175], v[200:203], v[18:21]
	v_mfma_f32_16x16x32_bf16 v[6:9], v[150:153], v[230:233], v[6:9]
	v_mfma_f32_16x16x32_bf16 v[2:5], v[172:175], v[230:233], v[2:5]
	s_setprio 0
	s_add_i32 s46, s46, 2
	s_add_u32 s34, s34, 0x100
	s_addc_u32 s35, s35, 0
	s_add_u32 s44, s44, 0x100
	s_addc_u32 s45, s45, 0
	s_cmp_gt_u32 s46, 29
	s_barrier
	s_cbranch_scc0 .LBB0_214

; #define PG8_STAGE(bufoff, gbase, voff) do { _Pragma("unroll") for (int _i = 0; _i < 2; ++_i) \
;         __builtin_amdgcn_global_load_lds((const unsigned*)((const char*)(gbase) + (voff)[_i]), (PG8_LAS unsigned*)(lds + (bufoff) + ldsw + _i * 8192), 16, 0, 0); } while (0)
; #define PG8_LDA(dst, b, h) do { _Pragma("unroll") for (int m = 0; m < 4; ++m) _Pragma("unroll") for (int k = 0; k < 2; ++k) dst[m][k] = *(const PG8_LAS bf16x8*)(lds + PG8_SA(b, h) + aoff + m * 2048 + k * 1024); } while (0)
; #define PG8_LDB(dst, b, h) do { _Pragma("unroll") for (int n = 0; n < 2; ++n) _Pragma("unroll") for (int k = 0; k < 2; ++k) dst[n][k] = *(const PG8_LAS bf16x8*)(lds + PG8_SB(b, h) + boff + n * 2048 + k * 1024); } while (0)
; #define PG8_WAIT_V(n) asm volatile("s_waitcnt vmcnt(" #n ")" ::: "memory")
; #define PG8_WAIT_L(n) asm volatile("s_waitcnt lgkmcnt(" #n ")" ::: "memory")
; #define PG8_BAR __builtin_amdgcn_s_barrier()
; #define PG8_SCHED __builtin_amdgcn_sched_barrier(0)
; template <class Epi, class Sched, bool ALIGN_EPI = false, bool SP2 = false>
; __device__ __forceinline__ void gemm_phase(PG8_LAS unsigned char* lds, const Gemm g, const Sched& S, const Epi& E) {
;     ...
;             PG8_LDB(B0, 0, 0); PG8_LDB(B1, 0, 1); PG8_SCHED; PG8_LDA(At, 0, 0); PG8_STAGE(PG8_SA(1, 1), a1 + hstep, voffA);
;             PG8_WAIT_V(8); PG8_WAIT_L(0); PG8_BAR; PG8_MMA(0, 0, At, B0); PG8_MMA(0, 1, At, B1); PG8_BAR; PG8_SCHED;
;             PG8_LDA(At, 0, 1); PG8_STAGE(PG8_SB(0, 0), b2, voffB); PG8_STAGE(PG8_SB(0, 1), b2 + hstep, voffB); PG8_STAGE(PG8_SA(0, 0), a2, voffA);
;             PG8_WAIT_V(8); PG8_WAIT_L(0); PG8_BAR; PG8_MMA(1, 0, At, B0); PG8_MMA(1, 1, At, B1); PG8_BAR; PG8_SCHED;
;     ...
;             PG8_LDB(B0, 0, 0); PG8_SCHED; PG8_LDA(At, 0, 0); PG8_STAGE(PG8_SA(1, 1), a1 + hstep, voffA);
;             PG8_WAIT_L(8); PG8_BAR; PG8_WAIT_L(0); PG8_MMA(0, 0, At, B0); PG8_BAR; PG8_SCHED;
;             PG8_LDB(B1, 0, 1); PG8_STAGE(PG8_SB(0, 0), b2, voffB);
;             PG8_BAR; PG8_WAIT_L(0); PG8_MMA(0, 1, At, B1); PG8_BAR;
;             PG8_LDA(At, 0, 1); PG8_STAGE(PG8_SA(0, 0), a2, voffA);
;             PG8_BAR; PG8_WAIT_L(0); PG8_MMA(1, 0, At, B0); PG8_BAR; PG8_SCHED;
;             PG8_STAGE(PG8_SB(0, 1), b2 + hstep, voffB);
;             PG8_WAIT_V(6); PG8_BAR; PG8_MMA(1, 1, At, B1); PG8_BAR;
.Ltail_loop:
	ds_read_b128 v[114:117], v242
	ds_read_b128 v[118:121], v242 offset:1024
	ds_read_b128 v[130:133], v242 offset:2048
	ds_read_b128 v[134:137], v242 offset:3072
	s_add_u32 s40, s34, 0xfff80080
	s_addc_u32 s41, s35, -1
	s_cmp_eq_u32 s46, 28
	s_cselect_b32 s43, s15, s41
	s_cselect_b32 s42, s19, s40
	s_cselect_b32 s41, s17, s45
	s_cselect_b32 s40, s37, s44
	v_lshl_add_u64 v[204:205], s[34:35], 0, v[164:165]
	s_add_i32 m0, s8, 0xc000
	ds_read_b128 v[180:183], v178
	ds_read_b128 v[184:187], v178 offset:1024
	ds_read_b128 v[188:191], v178 offset:2048
	ds_read_b128 v[192:195], v178 offset:3072
	ds_read_b128 v[196:199], v178 offset:4096
	ds_read_b128 v[200:203], v178 offset:5120
	ds_read_b128 v[208:211], v178 offset:6144
	ds_read_b128 v[230:233], v178 offset:7168
	global_load_lds_dwordx4 v[204:205], off
	s_add_i32 m0, s8, 0xe000
	v_lshl_add_u64 v[204:205], s[34:35], 0, v[166:167]
	global_load_lds_dwordx4 v[204:205], off
	s_waitcnt vmcnt(8)
	s_waitcnt lgkmcnt(0)
	s_barrier
	s_setprio 1
	v_mfma_f32_16x16x32_bf16 v[142:145], v[114:117], v[180:183], v[142:145]
	v_mfma_f32_16x16x32_bf16 v[138:141], v[130:133], v[180:183], v[138:141]
	v_mfma_f32_16x16x32_bf16 v[110:113], v[114:117], v[188:191], v[110:113]
	v_mfma_f32_16x16x32_bf16 v[106:109], v[130:133], v[188:191], v[106:109]
	v_mfma_f32_16x16x32_bf16 v[94:97], v[114:117], v[196:199], v[94:97]
	v_mfma_f32_16x16x32_bf16 v[90:93], v[130:133], v[196:199], v[90:93]
	v_mfma_f32_16x16x32_bf16 v[78:81], v[114:117], v[208:211], v[78:81]
	v_mfma_f32_16x16x32_bf16 v[74:77], v[130:133], v[208:211], v[74:77]
	v_mfma_f32_16x16x32_bf16 v[142:145], v[118:121], v[184:187], v[142:145]
	v_mfma_f32_16x16x32_bf16 v[138:141], v[134:137], v[184:187], v[138:141]
	v_mfma_f32_16x16x32_bf16 v[110:113], v[118:121], v[192:195], v[110:113]
	v_mfma_f32_16x16x32_bf16 v[106:109], v[134:137], v[192:195], v[106:109]
	v_mfma_f32_16x16x32_bf16 v[94:97], v[118:121], v[200:203], v[94:97]
	v_mfma_f32_16x16x32_bf16 v[90:93], v[134:137], v[200:203], v[90:93]
	v_mfma_f32_16x16x32_bf16 v[78:81], v[118:121], v[230:233], v[78:81]
	v_mfma_f32_16x16x32_bf16 v[74:77], v[134:137], v[230:233], v[74:77]
	s_setprio 0
	s_barrier
	s_add_i32 s47, s88, s6
	v_lshl_add_u64 v[204:205], s[40:41], 0, v[0:1]
	s_mov_b32 m0, s47
	ds_read_b128 v[180:183], v178 offset:16384
	ds_read_b128 v[184:187], v178 offset:17408
	ds_read_b128 v[188:191], v178 offset:18432
	ds_read_b128 v[192:195], v178 offset:19456
	ds_read_b128 v[196:199], v178 offset:20480
	ds_read_b128 v[200:203], v178 offset:21504
	ds_read_b128 v[208:211], v178 offset:22528
	ds_read_b128 v[230:233], v178 offset:23552
	global_load_lds_dwordx4 v[204:205], off
	s_add_i32 m0, s47, 0x2000
	s_add_u32 s50, s40, 0x80000
	v_lshl_add_u64 v[212:213], s[40:41], 0, v[154:155]
	s_addc_u32 s51, s41, 0
	s_add_i32 s47, s89, s6
	global_load_lds_dwordx4 v[212:213], off
	v_lshl_add_u64 v[234:235], s[50:51], 0, v[0:1]
	s_mov_b32 m0, s47
	v_lshl_add_u64 v[236:237], s[42:43], 0, v[156:157]
	global_load_lds_dwordx4 v[234:235], off
	s_add_i32 m0, s47, 0x2000
	v_lshl_add_u64 v[234:235], s[50:51], 0, v[154:155]
	global_load_lds_dwordx4 v[234:235], off
	s_mov_b32 m0, s8
	v_lshl_add_u64 v[234:235], s[42:43], 0, v[158:159]
	global_load_lds_dwordx4 v[234:235], off
	s_mov_b32 m0, s9
	s_nop 0
	global_load_lds_dwordx4 v[236:237], off
	s_waitcnt vmcnt(8)
	s_waitcnt lgkmcnt(0)
	s_barrier
	s_setprio 1
	v_mfma_f32_16x16x32_bf16 v[62:65], v[114:117], v[180:183], v[62:65]
	v_mfma_f32_16x16x32_bf16 v[58:61], v[130:133], v[180:183], v[58:61]
	v_mfma_f32_16x16x32_bf16 v[46:49], v[114:117], v[188:191], v[46:49]
	v_mfma_f32_16x16x32_bf16 v[42:45], v[130:133], v[188:191], v[42:45]
	v_mfma_f32_16x16x32_bf16 v[30:33], v[114:117], v[196:199], v[30:33]
	v_mfma_f32_16x16x32_bf16 v[26:29], v[130:133], v[196:199], v[26:29]
	v_mfma_f32_16x16x32_bf16 v[14:17], v[114:117], v[208:211], v[14:17]
	v_mfma_f32_16x16x32_bf16 v[10:13], v[130:133], v[208:211], v[10:13]
	v_mfma_f32_16x16x32_bf16 v[62:65], v[118:121], v[184:187], v[62:65]
	v_mfma_f32_16x16x32_bf16 v[58:61], v[134:137], v[184:187], v[58:61]
	v_mfma_f32_16x16x32_bf16 v[46:49], v[118:121], v[192:195], v[46:49]
	v_mfma_f32_16x16x32_bf16 v[42:45], v[134:137], v[192:195], v[42:45]
	v_mfma_f32_16x16x32_bf16 v[30:33], v[118:121], v[200:203], v[30:33]
	v_mfma_f32_16x16x32_bf16 v[26:29], v[134:137], v[200:203], v[26:29]
	v_mfma_f32_16x16x32_bf16 v[14:17], v[118:121], v[230:233], v[14:17]
	v_mfma_f32_16x16x32_bf16 v[10:13], v[134:137], v[230:233], v[10:13]
	s_setprio 0
	s_barrier
; #define PG8_STAGE(bufoff, gbase, voff) do { _Pragma("unroll") for (int _i = 0; _i < 2; ++_i) \
;         __builtin_amdgcn_global_load_lds((const unsigned*)((const char*)(gbase) + (voff)[_i]), (PG8_LAS unsigned*)(lds + (bufoff) + ldsw + _i * 8192), 16, 0, 0); } while (0)
; #define PG8_LDA(dst, b, h) do { _Pragma("unroll") for (int m = 0; m < 4; ++m) _Pragma("unroll") for (int k = 0; k < 2; ++k) dst[m][k] = *(const PG8_LAS bf16x8*)(lds + PG8_SA(b, h) + aoff + m * 2048 + k * 1024); } while (0)
; #define PG8_LDB(dst, b, h) do { _Pragma("unroll") for (int n = 0; n < 2; ++n) _Pragma("unroll") for (int k = 0; k < 2; ++k) dst[n][k] = *(const PG8_LAS bf16x8*)(lds + PG8_SB(b, h) + boff + n * 2048 + k * 1024); } while (0)
; #define PG8_MMA(ai, bj, At, Bt) do { __builtin_amdgcn_s_setprio(1); _Pragma("unroll") for (int m = 0; m < 4; ++m) _Pragma("unroll") for (int n = 0; n < 2; ++n) _Pragma("unroll") for (int k = 0; k < 2; ++k) \
;         acc[ai][bj][m][n] = __builtin_amdgcn_mfma_f32_16x16x32_bf16(Bt[n][k], At[m][k], acc[ai][bj][m][n], 0, 0, 0); __builtin_amdgcn_s_setprio(0); } while (0)
; #define PG8_WAIT_V(n) asm volatile("s_waitcnt vmcnt(" #n ")" ::: "memory")
; #define PG8_WAIT_L(n) asm volatile("s_waitcnt lgkmcnt(" #n ")" ::: "memory")
; #define PG8_BAR __builtin_amdgcn_s_barrier()
; template <class Epi, class Sched, bool ALIGN_EPI = false, bool SP2 = false>
; __device__ __forceinline__ void gemm_phase(PG8_LAS unsigned char* lds, const Gemm g, const Sched& S, const Epi& E) {
;     ...
;         for (int t = 0; t < nt; t += 2) {
;             const bool last = (t == nt - 2);
;             const char* a1 = cA + (size_t)(t + 1) * kstep;
;             const char* a2 = last ? nA : cA + (size_t)(t + 2) * kstep; const char* b2 = last ? nB : cB + (size_t)(t + 2) * kstep;
;     ...
;             PG8_LDB(B0, 1, 0); PG8_SCHED; PG8_LDA(At, 1, 0); PG8_STAGE(PG8_SA(0, 1), a2 + hstep, voffA);
;             PG8_WAIT_L(8); PG8_BAR; PG8_WAIT_L(0); PG8_MMA(0, 0, At, B0); PG8_BAR; PG8_SCHED;
;             PG8_LDB(B1, 1, 1); PG8_STAGE(PG8_SB(1, 0), b3, voffB);
;             PG8_BAR; PG8_WAIT_L(0); PG8_MMA(0, 1, At, B1); PG8_BAR;
;             PG8_LDA(At, 1, 1); PG8_STAGE(PG8_SA(1, 0), a3, voffA);
;             PG8_BAR; PG8_WAIT_L(0); PG8_MMA(1, 0, At, B0); PG8_BAR; PG8_SCHED;
;             PG8_STAGE(PG8_SB(1, 1), b3 + hstep, voffB);
;             PG8_WAIT_V(6); PG8_BAR; PG8_MMA(1, 1, At, B1); PG8_BAR;
	s_add_i32 s47, 0, 0x1c000
	ds_read_b128 v[114:117], v244
	ds_read_b128 v[118:121], v244 offset:1024
	ds_read_b128 v[130:133], v244 offset:2048
	ds_read_b128 v[134:137], v244 offset:3072
	s_add_u32 s42, s42, 0x80000
	s_addc_u32 s43, s43, 0
	s_mov_b32 m0, s10
	v_lshl_add_u64 v[238:239], s[42:43], 0, v[158:159]
	ds_read_b128 v[180:183], v178 offset:32768
	ds_read_b128 v[184:187], v178 offset:33792
	ds_read_b128 v[188:191], v178 offset:34816
	ds_read_b128 v[192:195], v178 offset:35840
	ds_read_b128 v[196:199], v178 offset:36864
	ds_read_b128 v[200:203], v178 offset:37888
	ds_read_b128 v[208:211], v178 offset:38912
	ds_read_b128 v[230:233], v178 offset:39936
	global_load_lds_dwordx4 v[238:239], off
	s_mov_b32 m0, s11
	v_lshl_add_u64 v[238:239], s[42:43], 0, v[156:157]
	global_load_lds_dwordx4 v[238:239], off
	s_waitcnt vmcnt(8)
	s_waitcnt lgkmcnt(0)
	s_barrier
	s_setprio 1
	v_mfma_f32_16x16x32_bf16 v[142:145], v[114:117], v[180:183], v[142:145]
	v_mfma_f32_16x16x32_bf16 v[138:141], v[130:133], v[180:183], v[138:141]
	v_mfma_f32_16x16x32_bf16 v[110:113], v[114:117], v[188:191], v[110:113]
	v_mfma_f32_16x16x32_bf16 v[106:109], v[130:133], v[188:191], v[106:109]
	v_mfma_f32_16x16x32_bf16 v[94:97], v[114:117], v[196:199], v[94:97]
	v_mfma_f32_16x16x32_bf16 v[90:93], v[130:133], v[196:199], v[90:93]
	v_mfma_f32_16x16x32_bf16 v[78:81], v[114:117], v[208:211], v[78:81]
	v_mfma_f32_16x16x32_bf16 v[74:77], v[130:133], v[208:211], v[74:77]
	v_mfma_f32_16x16x32_bf16 v[142:145], v[118:121], v[184:187], v[142:145]
	v_mfma_f32_16x16x32_bf16 v[138:141], v[134:137], v[184:187], v[138:141]
	v_mfma_f32_16x16x32_bf16 v[110:113], v[118:121], v[192:195], v[110:113]
	v_mfma_f32_16x16x32_bf16 v[106:109], v[134:137], v[192:195], v[106:109]
	v_mfma_f32_16x16x32_bf16 v[94:97], v[118:121], v[200:203], v[94:97]
	v_mfma_f32_16x16x32_bf16 v[90:93], v[134:137], v[200:203], v[90:93]
	v_mfma_f32_16x16x32_bf16 v[78:81], v[118:121], v[230:233], v[78:81]
	v_mfma_f32_16x16x32_bf16 v[74:77], v[134:137], v[230:233], v[74:77]
	s_setprio 0
	s_barrier
	s_add_i32 s42, s90, s6
	v_lshl_add_u64 v[204:205], v[204:205], 0, s[70:71]
	s_mov_b32 m0, s42
	ds_read_b128 v[180:183], v178 offset:49152
	ds_read_b128 v[184:187], v178 offset:50176
	ds_read_b128 v[188:191], v178 offset:51200
	ds_read_b128 v[192:195], v178 offset:52224
	ds_read_b128 v[196:199], v178 offset:53248
	ds_read_b128 v[200:203], v178 offset:54272
	ds_read_b128 v[208:211], v178 offset:55296
	ds_read_b128 v[230:233], v178 offset:56320
	global_load_lds_dwordx4 v[204:205], off
	s_add_i32 m0, s42, 0x2000
	s_add_u32 s40, s40, 0x80080
	v_lshl_add_u64 v[204:205], v[212:213], 0, s[70:71]
	s_addc_u32 s41, s41, 0
	s_add_i32 s42, s47, s6
	global_load_lds_dwordx4 v[204:205], off
	s_mov_b32 m0, s42
	v_lshl_add_u64 v[204:205], s[40:41], 0, v[0:1]
	global_load_lds_dwordx4 v[204:205], off
	s_add_i32 m0, s42, 0x2000
	v_lshl_add_u64 v[204:205], s[40:41], 0, v[154:155]
	global_load_lds_dwordx4 v[204:205], off
	s_mov_b32 m0, s13
	v_lshl_add_u64 v[204:205], v[234:235], 0, s[70:71]
	global_load_lds_dwordx4 v[204:205], off
	s_mov_b32 m0, s25
	v_lshl_add_u64 v[204:205], v[236:237], 0, s[70:71]
	global_load_lds_dwordx4 v[204:205], off
	s_waitcnt vmcnt(8)
	s_waitcnt lgkmcnt(0)
	s_barrier
	s_setprio 1
	v_mfma_f32_16x16x32_bf16 v[62:65], v[114:117], v[180:183], v[62:65]
	v_mfma_f32_16x16x32_bf16 v[58:61], v[130:133], v[180:183], v[58:61]
	v_mfma_f32_16x16x32_bf16 v[46:49], v[114:117], v[188:191], v[46:49]
	v_mfma_f32_16x16x32_bf16 v[42:45], v[130:133], v[188:191], v[42:45]
	v_mfma_f32_16x16x32_bf16 v[30:33], v[114:117], v[196:199], v[30:33]
	v_mfma_f32_16x16x32_bf16 v[26:29], v[130:133], v[196:199], v[26:29]
	v_mfma_f32_16x16x32_bf16 v[14:17], v[114:117], v[208:211], v[14:17]
	v_mfma_f32_16x16x32_bf16 v[10:13], v[130:133], v[208:211], v[10:13]
	v_mfma_f32_16x16x32_bf16 v[62:65], v[118:121], v[184:187], v[62:65]
	v_mfma_f32_16x16x32_bf16 v[58:61], v[134:137], v[184:187], v[58:61]
	v_mfma_f32_16x16x32_bf16 v[46:49], v[118:121], v[192:195], v[46:49]
	v_mfma_f32_16x16x32_bf16 v[42:45], v[134:137], v[192:195], v[42:45]
	v_mfma_f32_16x16x32_bf16 v[30:33], v[118:121], v[200:203], v[30:33]
	v_mfma_f32_16x16x32_bf16 v[26:29], v[134:137], v[200:203], v[26:29]
	v_mfma_f32_16x16x32_bf16 v[14:17], v[118:121], v[230:233], v[14:17]
	v_mfma_f32_16x16x32_bf16 v[10:13], v[134:137], v[230:233], v[10:13]
	s_setprio 0
	s_add_i32 s46, s46, 2
	s_add_u32 s34, s34, 0x100
	s_addc_u32 s35, s35, 0
	s_add_u32 s44, s44, 0x100
	s_addc_u32 s45, s45, 0
	s_cmp_gt_u32 s46, 29
	s_barrier
	s_cbranch_scc0 .Ltail_loop
	s_branch .Ltail_join
